# phase 3 head-tile epilogue: rope table loads of each row group issued at the start of its norm block (hidden under the sum-of-squares reduction)
# baseline (speedup 1.0000x reference)
;     DI void operator()(Acc& acc, const pg8::Unit& u, int wr, int wc, int fr, int fq, const Pre& pr) const {
;     ...
;                     const int row = u.pm * 256 + ai * 128 + wr * 64 + m * 16 + fr;
;                     const float rs = __builtin_amdgcn_rsqf(msq_of(pr.v[ai * 4 + m]));
;                     f32x4 v[2][2];
; #pragma unroll
;                     for (int bj = 0; bj < 2; ++bj)
; #pragma unroll
;                         for (int n = 0; n < 2; ++n) v[bj][n] = acc[ai][bj][m][n] * rs;
;                     if (do_norm) {
;                         float ss = 0.f;
; #pragma unroll
;                         for (int bj = 0; bj < 2; ++bj)
; #pragma unroll
;                             for (int n = 0; n < 2; ++n) ss += (v[bj][n][0] * v[bj][n][0] + v[bj][n][1] * v[bj][n][1]) + (v[bj][n][2] * v[bj][n][2] + v[bj][n][3] * v[bj][n][3]);
;                         ss += __shfl_xor(ss, 16); ss += __shfl_xor(ss, 32);
;                         const float hr = __builtin_amdgcn_rsqf(ss * (1.0f / 64.0f) + NORM_EPS);
; #pragma unroll
;                         for (int bj = 0; bj < 2; ++bj)
; #pragma unroll
;                             for (int n = 0; n < 2; ++n) v[bj][n] = v[bj][n] * hr * gn[bj][n];
;                         const int s = row & (SEQ - 1);
; #pragma unroll
;                         for (int n = 0; n < 2; ++n) {
;                             f32x4 pr;
; #pragma unroll
;                             for (int i = 0; i < 4; ++i) pr[i] = __shfl_xor(v[0][n][i], 16);
;                             if (fq < 2) {
;                                 const f32x4 cs = *(const f32x4*)(rope + s * 16 + 4 * n), sn = *(const f32x4*)(rope + s * 16 + 8 + 4 * n);
;                                 v[0][n] = (fq == 0) ? (v[0][n] * cs - pr * sn) : (v[0][n] * cs + pr * sn);
;                             }
;                         }
.LBB0_413:
	s_waitcnt vmcnt(0)
	v_fmamk_f32 v156, v174, 0x3a800000, v187
	v_rsq_f32_e32 v156, v156
	s_and_b64 vcc, exec, s[10:11]
	v_pk_mul_f32 v[128:129], v[156:157], v[128:129] op_sel_hi:[0,1]
	v_pk_mul_f32 v[126:127], v[156:157], v[126:127] op_sel_hi:[0,1]
	v_pk_mul_f32 v[124:125], v[156:157], v[124:125] op_sel_hi:[0,1]
	v_pk_mul_f32 v[122:123], v[156:157], v[122:123] op_sel_hi:[0,1]
	v_pk_mul_f32 v[120:121], v[156:157], v[120:121] op_sel_hi:[0,1]
	v_pk_mul_f32 v[118:119], v[156:157], v[118:119] op_sel_hi:[0,1]
	v_pk_mul_f32 v[116:117], v[156:157], v[116:117] op_sel_hi:[0,1]
	v_pk_mul_f32 v[114:115], v[156:157], v[114:115] op_sel_hi:[0,1]
	s_cbranch_vccnz .LBB0_419
	v_lshlrev_b32_e32 v222, 6, v170
	v_and_b32_e32 v222, 0x1ffc0, v222
	global_load_dwordx4 v[206:209], v222, s[40:41] offset:32
	global_load_dwordx4 v[210:213], v222, s[40:41]
	global_load_dwordx4 v[214:217], v222, s[40:41] offset:48
	global_load_dwordx4 v[218:221], v222, s[40:41] offset:16
	v_pk_mul_f32 v[172:173], v[128:129], v[128:129]
	v_pk_mul_f32 v[174:175], v[126:127], v[126:127]
	v_mul_f32_e32 v156, v114, v114
	v_pk_mov_b32 v[176:177], v[174:175], v[172:173] op_sel:[1,0]
	v_mov_b32_e32 v175, v173
	v_pk_add_f32 v[172:173], v[176:177], v[174:175]
	v_pk_mul_f32 v[174:175], v[124:125], v[124:125]
	v_pk_mul_f32 v[176:177], v[122:123], v[122:123]
	v_pk_add_f32 v[172:173], v[172:173], v[172:173] op_sel:[0,1] op_sel_hi:[1,0]
	v_pk_mov_b32 v[178:179], v[176:177], v[174:175] op_sel:[1,0]
	v_mov_b32_e32 v177, v175
	v_pk_add_f32 v[174:175], v[178:179], v[176:177]
	v_mul_f32_e32 v176, v115, v115
	v_pk_add_f32 v[174:175], v[174:175], v[174:175] op_sel:[0,1] op_sel_hi:[1,0]
	v_mov_b32_e32 v173, v156
	v_mov_b32_e32 v175, v176
	v_mul_f32_e32 v156, v119, v119
	v_mul_f32_e32 v177, v116, v116
	v_pk_add_f32 v[172:173], v[172:173], v[174:175]
	v_pk_fma_f32 v[174:175], v[118:119], v[118:119], v[156:157] op_sel_hi:[1,1,0]
	v_mul_f32_e32 v156, v121, v121
	v_mul_f32_e32 v178, v117, v117
	v_mov_b32_e32 v175, v177
	v_pk_fma_f32 v[176:177], v[120:121], v[120:121], v[156:157] op_sel_hi:[1,1,0]
	s_nop 0
	v_mov_b32_e32 v177, v178
	v_pk_add_f32 v[174:175], v[174:175], v[176:177]
	s_nop 0
	v_pk_add_f32 v[172:173], v[172:173], v[174:175]
	s_nop 0
	v_add_f32_e32 v156, v172, v173
	v_and_b32_e32 v173, 64, v190
	v_xor_b32_e32 v172, 16, v190
	v_add_u32_e32 v173, 64, v173
	v_cmp_lt_i32_e32 vcc, v172, v173
	s_nop 1
	v_cndmask_b32_e32 v172, v190, v172, vcc
	v_lshlrev_b32_e32 v181, 2, v172
	ds_bpermute_b32 v172, v181, v156
	s_waitcnt lgkmcnt(0)
	v_add_f32_e32 v156, v156, v172
	v_xor_b32_e32 v172, 32, v190
	v_cmp_lt_i32_e32 vcc, v172, v173
	s_nop 1
	v_cndmask_b32_e32 v172, v190, v172, vcc
	v_lshlrev_b32_e32 v172, 2, v172
	ds_bpermute_b32 v172, v172, v156
	s_waitcnt lgkmcnt(0)
	v_add_f32_e32 v156, v156, v172
	v_fmamk_f32 v156, v156, 0x3c800000, v187
	v_rsq_f32_e32 v172, v156
	v_lshlrev_b32_e32 v156, 6, v170
	v_and_b32_e32 v156, 0x1f3c0, v156
	v_lshl_add_u64 v[176:177], s[40:41], 0, v[156:157]
	v_pk_mul_f32 v[126:127], v[126:127], v[172:173] op_sel_hi:[1,0]
	v_pk_mul_f32 v[128:129], v[128:129], v[172:173] op_sel_hi:[1,0]
	v_pk_mul_f32 v[126:127], v[142:143], v[126:127]
	v_pk_mul_f32 v[128:129], v[144:145], v[128:129]
	ds_bpermute_b32 v174, v181, v126
	ds_bpermute_b32 v175, v181, v127
	ds_bpermute_b32 v178, v181, v128
	ds_bpermute_b32 v179, v181, v129
	s_and_saveexec_b64 s[68:69], s[4:5]
	s_cbranch_execz .LBB0_416
	s_waitcnt vmcnt(2)
	v_mov_b64_e32 v[198:199], v[206:207]
	v_mov_b64_e32 v[200:201], v[208:209]
	v_mov_b64_e32 v[202:203], v[210:211]
	v_mov_b64_e32 v[204:205], v[212:213]
	s_waitcnt lgkmcnt(0)
	v_pk_mul_f32 v[178:179], v[200:201], v[178:179]
	v_pk_mul_f32 v[174:175], v[198:199], v[174:175]
	v_xor_b32_e32 v156, 0x80000000, v178
	v_xor_b32_e32 v173, 0x80000000, v179
	v_xor_b32_e32 v180, 0x80000000, v174
	v_xor_b32_e32 v198, 0x80000000, v175
	v_cndmask_b32_e64 v179, v179, v173, s[6:7]
	v_cndmask_b32_e64 v178, v178, v156, s[6:7]
	v_cndmask_b32_e64 v175, v175, v198, s[6:7]
	v_cndmask_b32_e64 v174, v174, v180, s[6:7]
	v_pk_fma_f32 v[128:129], v[128:129], v[204:205], v[178:179]
	v_pk_fma_f32 v[126:127], v[126:127], v[202:203], v[174:175]
.LBB0_416:
	s_or_b64 exec, exec, s[68:69]
	v_mov_b32_e32 v173, v172
	s_waitcnt lgkmcnt(3)
	v_mov_b32_e32 v174, v172
	s_waitcnt lgkmcnt(2)
	v_mov_b32_e32 v175, v172
	v_pk_mul_f32 v[124:125], v[124:125], v[174:175]
	v_pk_mul_f32 v[122:123], v[122:123], v[172:173]
	v_pk_mul_f32 v[124:125], v[140:141], v[124:125]
	v_pk_mul_f32 v[122:123], v[138:139], v[122:123]
	s_waitcnt lgkmcnt(1)
	ds_bpermute_b32 v178, v181, v122
	s_waitcnt lgkmcnt(1)
	ds_bpermute_b32 v179, v181, v123
	ds_bpermute_b32 v180, v181, v124
	ds_bpermute_b32 v181, v181, v125
	s_and_saveexec_b64 s[68:69], s[4:5]
	s_cbranch_execz .LBB0_418
	s_waitcnt vmcnt(0)
	v_mov_b64_e32 v[198:199], v[214:215]
	v_mov_b64_e32 v[200:201], v[216:217]
	v_mov_b64_e32 v[202:203], v[218:219]
	v_mov_b64_e32 v[204:205], v[220:221]
	s_waitcnt lgkmcnt(0)
	v_pk_mul_f32 v[176:177], v[200:201], v[180:181]
	v_pk_mul_f32 v[178:179], v[198:199], v[178:179]
	v_xor_b32_e32 v156, 0x80000000, v176
	v_xor_b32_e32 v180, 0x80000000, v177
	v_xor_b32_e32 v181, 0x80000000, v178
	v_xor_b32_e32 v198, 0x80000000, v179
	v_cndmask_b32_e64 v177, v177, v180, s[6:7]
	v_cndmask_b32_e64 v176, v176, v156, s[6:7]
	v_cndmask_b32_e64 v179, v179, v198, s[6:7]
	v_cndmask_b32_e64 v178, v178, v181, s[6:7]
	v_pk_fma_f32 v[124:125], v[124:125], v[204:205], v[176:177]
	v_pk_fma_f32 v[122:123], v[122:123], v[202:203], v[178:179]

;     DI void operator()(Acc& acc, const pg8::Unit& u, int wr, int wc, int fr, int fq, const Pre& pr) const {
;     ...
;                     const int row = u.pm * 256 + ai * 128 + wr * 64 + m * 16 + fr;
;                     const float rs = __builtin_amdgcn_rsqf(msq_of(pr.v[ai * 4 + m]));
;                     f32x4 v[2][2];
; #pragma unroll
;                     for (int bj = 0; bj < 2; ++bj)
; #pragma unroll
;                         for (int n = 0; n < 2; ++n) v[bj][n] = acc[ai][bj][m][n] * rs;
;                     if (do_norm) {
;                         float ss = 0.f;
; #pragma unroll
;                         for (int bj = 0; bj < 2; ++bj)
; #pragma unroll
;                             for (int n = 0; n < 2; ++n) ss += (v[bj][n][0] * v[bj][n][0] + v[bj][n][1] * v[bj][n][1]) + (v[bj][n][2] * v[bj][n][2] + v[bj][n][3] * v[bj][n][3]);
;                         ss += __shfl_xor(ss, 16); ss += __shfl_xor(ss, 32);
;                         const float hr = __builtin_amdgcn_rsqf(ss * (1.0f / 64.0f) + NORM_EPS);
; #pragma unroll
;                         for (int bj = 0; bj < 2; ++bj)
; #pragma unroll
;                             for (int n = 0; n < 2; ++n) v[bj][n] = v[bj][n] * hr * gn[bj][n];
;                         const int s = row & (SEQ - 1);
; #pragma unroll
;                         for (int n = 0; n < 2; ++n) {
;                             f32x4 pr;
; #pragma unroll
;                             for (int i = 0; i < 4; ++i) pr[i] = __shfl_xor(v[0][n][i], 16);
;                             if (fq < 2) {
;                                 const f32x4 cs = *(const f32x4*)(rope + s * 16 + 4 * n), sn = *(const f32x4*)(rope + s * 16 + 8 + 4 * n);
;                                 v[0][n] = (fq == 0) ? (v[0][n] * cs - pr * sn) : (v[0][n] * cs + pr * sn);
;                             }
;                         }
;                     }
;                     bf16_t* dst;
;                     if (pn < 2) dst = Q + (size_t)row * 512 + (4 * pn + wc) * 64 + 8 * fq;
;                     else { const int b = row >> 11, sq = row & (SEQ - 1); dst = KV + (size_t)slot * KV_SLOT + ((size_t)((b * 2 + gidx) * SEQ + sq)) * 64 + 8 * fq; }
; #pragma unroll
;                     for (int bj = 0; bj < 2; ++bj) store8(dst + 32 * bj, v[bj][0] * scale, v[bj][1] * scale);
.LBB0_423:
	v_lshlrev_b32_e32 v156, 1, v158
	v_pk_mul_f32 v[128:129], s[64:65], v[128:129] op_sel_hi:[0,1]
	v_pk_mul_f32 v[126:127], s[64:65], v[126:127] op_sel_hi:[0,1]
	v_pk_mul_f32 v[174:175], s[64:65], v[124:125] op_sel_hi:[0,1]
	v_pk_mul_f32 v[124:125], s[64:65], v[122:123] op_sel_hi:[0,1]
	v_lshl_add_u64 v[172:173], v[172:173], 0, v[156:157]
	v_cvt_pk_bf16_f32 v122, v126, v127
	v_cvt_pk_bf16_f32 v123, v128, v129
	v_cvt_pk_bf16_f32 v124, v124, v125
	v_cvt_pk_bf16_f32 v125, v174, v175
	v_pk_mul_f32 v[118:119], s[64:65], v[118:119] op_sel_hi:[0,1]
	global_store_dwordx4 v[172:173], v[122:125], off
	v_pk_mul_f32 v[120:121], s[64:65], v[120:121] op_sel_hi:[0,1]
	s_and_b64 vcc, exec, s[10:11]
	v_pk_mul_f32 v[122:123], s[64:65], v[116:117] op_sel_hi:[0,1]
	v_pk_mul_f32 v[116:117], s[64:65], v[114:115] op_sel_hi:[0,1]
	v_cvt_pk_bf16_f32 v114, v118, v119
	v_fmamk_f32 v118, v197, 0x3a800000, v187
	v_rsq_f32_e32 v118, v118
	v_cvt_pk_bf16_f32 v115, v120, v121
	v_cvt_pk_bf16_f32 v116, v116, v117
	v_cvt_pk_bf16_f32 v117, v122, v123
	global_store_dwordx4 v[172:173], v[114:117], off offset:64
	v_pk_mul_f32 v[112:113], v[118:119], v[112:113] op_sel_hi:[0,1]
	v_pk_mul_f32 v[110:111], v[118:119], v[110:111] op_sel_hi:[0,1]
	v_pk_mul_f32 v[108:109], v[118:119], v[108:109] op_sel_hi:[0,1]
	v_pk_mul_f32 v[106:107], v[118:119], v[106:107] op_sel_hi:[0,1]
	v_pk_mul_f32 v[104:105], v[118:119], v[104:105] op_sel_hi:[0,1]
	v_pk_mul_f32 v[102:103], v[118:119], v[102:103] op_sel_hi:[0,1]
	v_pk_mul_f32 v[100:101], v[118:119], v[100:101] op_sel_hi:[0,1]
	v_pk_mul_f32 v[98:99], v[118:119], v[98:99] op_sel_hi:[0,1]
	v_or_b32_e32 v114, 16, v170
	s_cbranch_vccnz .LBB0_429
	v_lshlrev_b32_e32 v222, 6, v114
	v_and_b32_e32 v222, 0x1ffc0, v222
	global_load_dwordx4 v[206:209], v222, s[40:41] offset:32
	global_load_dwordx4 v[210:213], v222, s[40:41]
	global_load_dwordx4 v[214:217], v222, s[40:41] offset:48
	global_load_dwordx4 v[218:221], v222, s[40:41] offset:16
	v_pk_mul_f32 v[116:117], v[112:113], v[112:113]
	v_pk_mul_f32 v[118:119], v[110:111], v[110:111]
	v_mul_f32_e32 v115, v98, v98
	v_pk_mov_b32 v[120:121], v[118:119], v[116:117] op_sel:[1,0]
	v_mov_b32_e32 v119, v117
	v_pk_add_f32 v[116:117], v[120:121], v[118:119]
	v_pk_mul_f32 v[118:119], v[108:109], v[108:109]
	v_pk_mul_f32 v[120:121], v[106:107], v[106:107]
	v_pk_add_f32 v[116:117], v[116:117], v[116:117] op_sel:[0,1] op_sel_hi:[1,0]
	v_pk_mov_b32 v[122:123], v[120:121], v[118:119] op_sel:[1,0]
	v_mov_b32_e32 v121, v119
	v_pk_add_f32 v[118:119], v[122:123], v[120:121]
	v_mul_f32_e32 v120, v99, v99
	v_pk_add_f32 v[118:119], v[118:119], v[118:119] op_sel:[0,1] op_sel_hi:[1,0]
	v_mov_b32_e32 v117, v115
	v_mov_b32_e32 v119, v120
	v_pk_add_f32 v[116:117], v[116:117], v[118:119]
	v_mul_f32_e32 v118, v103, v103
	v_mul_f32_e32 v121, v100, v100
	v_pk_fma_f32 v[118:119], v[102:103], v[102:103], v[118:119] op_sel_hi:[1,1,0]
	v_mul_f32_e32 v120, v105, v105
	v_mul_f32_e32 v122, v101, v101
	v_mov_b32_e32 v119, v121
	v_pk_fma_f32 v[120:121], v[104:105], v[104:105], v[120:121] op_sel_hi:[1,1,0]
	v_xor_b32_e32 v115, 16, v190
	v_mov_b32_e32 v121, v122
	v_pk_add_f32 v[118:119], v[118:119], v[120:121]
	v_mov_b32_e32 v121, v157
	v_pk_add_f32 v[116:117], v[116:117], v[118:119]
	s_nop 0
	v_add_f32_e32 v116, v116, v117
	v_and_b32_e32 v117, 64, v190
	v_add_u32_e32 v117, 64, v117
	v_cmp_lt_i32_e32 vcc, v115, v117
	s_nop 1
	v_cndmask_b32_e32 v115, v190, v115, vcc
	v_lshlrev_b32_e32 v115, 2, v115
	ds_bpermute_b32 v118, v115, v116
	s_waitcnt lgkmcnt(0)
	v_add_f32_e32 v116, v116, v118
	v_xor_b32_e32 v118, 32, v190
	v_cmp_lt_i32_e32 vcc, v118, v117
	s_nop 1
	v_cndmask_b32_e32 v117, v190, v118, vcc
	v_lshlrev_b32_e32 v117, 2, v117
	ds_bpermute_b32 v117, v117, v116
	s_waitcnt lgkmcnt(0)
	v_add_f32_e32 v116, v116, v117
	v_fmamk_f32 v116, v116, 0x3c800000, v187
	v_rsq_f32_e32 v116, v116
	s_nop 0
	v_pk_mul_f32 v[110:111], v[110:111], v[116:117] op_sel_hi:[1,0]
	v_pk_mul_f32 v[112:113], v[112:113], v[116:117] op_sel_hi:[1,0]
	v_pk_mul_f32 v[110:111], v[142:143], v[110:111]
	v_pk_mul_f32 v[112:113], v[144:145], v[112:113]
	ds_bpermute_b32 v118, v115, v110
	ds_bpermute_b32 v119, v115, v111
	ds_bpermute_b32 v122, v115, v112
	ds_bpermute_b32 v123, v115, v113
	v_lshlrev_b32_e32 v117, 6, v114
	v_and_b32_e32 v120, 0x1f7c0, v117
	v_lshl_add_u64 v[120:121], s[40:41], 0, v[120:121]
	s_and_saveexec_b64 s[12:13], s[4:5]
	s_cbranch_execz .LBB0_426
	s_waitcnt vmcnt(2)
	v_mov_b64_e32 v[124:125], v[206:207]
	v_mov_b64_e32 v[126:127], v[208:209]
	v_mov_b64_e32 v[172:173], v[210:211]
	v_mov_b64_e32 v[174:175], v[212:213]
	s_waitcnt lgkmcnt(0)
	v_pk_mul_f32 v[122:123], v[126:127], v[122:123]
	v_pk_mul_f32 v[118:119], v[124:125], v[118:119]
	v_xor_b32_e32 v117, 0x80000000, v122
	v_xor_b32_e32 v124, 0x80000000, v123
	v_xor_b32_e32 v125, 0x80000000, v118
	v_xor_b32_e32 v126, 0x80000000, v119
	v_cndmask_b32_e64 v123, v123, v124, s[6:7]
	v_cndmask_b32_e64 v122, v122, v117, s[6:7]
	v_cndmask_b32_e64 v119, v119, v126, s[6:7]
	v_cndmask_b32_e64 v118, v118, v125, s[6:7]
	v_pk_fma_f32 v[112:113], v[112:113], v[174:175], v[122:123]
	v_pk_fma_f32 v[110:111], v[110:111], v[172:173], v[118:119]
.LBB0_426:
	s_or_b64 exec, exec, s[12:13]
	v_mov_b32_e32 v117, v116
	s_waitcnt lgkmcnt(3)
	v_mov_b32_e32 v118, v116
	s_waitcnt lgkmcnt(2)
	v_mov_b32_e32 v119, v116
	v_pk_mul_f32 v[108:109], v[108:109], v[118:119]
	v_pk_mul_f32 v[106:107], v[106:107], v[116:117]
	v_pk_mul_f32 v[108:109], v[140:141], v[108:109]
	v_pk_mul_f32 v[106:107], v[138:139], v[106:107]
	s_waitcnt lgkmcnt(1)
	ds_bpermute_b32 v122, v115, v106
	s_waitcnt lgkmcnt(1)
	ds_bpermute_b32 v123, v115, v107
	ds_bpermute_b32 v124, v115, v108
	ds_bpermute_b32 v125, v115, v109
	s_and_saveexec_b64 s[12:13], s[4:5]
	s_cbranch_execz .LBB0_428
	s_waitcnt vmcnt(0)
	v_mov_b64_e32 v[126:127], v[214:215]
	v_mov_b64_e32 v[128:129], v[216:217]
	v_mov_b64_e32 v[172:173], v[218:219]
	v_mov_b64_e32 v[174:175], v[220:221]
	s_waitcnt lgkmcnt(0)
	v_pk_mul_f32 v[120:121], v[128:129], v[124:125]
	v_pk_mul_f32 v[122:123], v[126:127], v[122:123]
	v_xor_b32_e32 v115, 0x80000000, v120
	v_xor_b32_e32 v124, 0x80000000, v121
	v_xor_b32_e32 v125, 0x80000000, v122
	v_xor_b32_e32 v126, 0x80000000, v123
	v_cndmask_b32_e64 v121, v121, v124, s[6:7]
	v_cndmask_b32_e64 v120, v120, v115, s[6:7]
	v_cndmask_b32_e64 v123, v123, v126, s[6:7]
	v_cndmask_b32_e64 v122, v122, v125, s[6:7]
	v_pk_fma_f32 v[108:109], v[108:109], v[174:175], v[120:121]
	v_pk_fma_f32 v[106:107], v[106:107], v[172:173], v[122:123]

;     DI void operator()(Acc& acc, const pg8::Unit& u, int wr, int wc, int fr, int fq, const Pre& pr) const {
;     ...
;                     const int row = u.pm * 256 + ai * 128 + wr * 64 + m * 16 + fr;
;                     const float rs = __builtin_amdgcn_rsqf(msq_of(pr.v[ai * 4 + m]));
;                     f32x4 v[2][2];
; #pragma unroll
;                     for (int bj = 0; bj < 2; ++bj)
; #pragma unroll
;                         for (int n = 0; n < 2; ++n) v[bj][n] = acc[ai][bj][m][n] * rs;
;                     if (do_norm) {
;                         float ss = 0.f;
; #pragma unroll
;                         for (int bj = 0; bj < 2; ++bj)
; #pragma unroll
;                             for (int n = 0; n < 2; ++n) ss += (v[bj][n][0] * v[bj][n][0] + v[bj][n][1] * v[bj][n][1]) + (v[bj][n][2] * v[bj][n][2] + v[bj][n][3] * v[bj][n][3]);
;                         ss += __shfl_xor(ss, 16); ss += __shfl_xor(ss, 32);
;                         const float hr = __builtin_amdgcn_rsqf(ss * (1.0f / 64.0f) + NORM_EPS);
; #pragma unroll
;                         for (int bj = 0; bj < 2; ++bj)
; #pragma unroll
;                             for (int n = 0; n < 2; ++n) v[bj][n] = v[bj][n] * hr * gn[bj][n];
;                         const int s = row & (SEQ - 1);
; #pragma unroll
;                         for (int n = 0; n < 2; ++n) {
;                             f32x4 pr;
; #pragma unroll
;                             for (int i = 0; i < 4; ++i) pr[i] = __shfl_xor(v[0][n][i], 16);
;                             if (fq < 2) {
;                                 const f32x4 cs = *(const f32x4*)(rope + s * 16 + 4 * n), sn = *(const f32x4*)(rope + s * 16 + 8 + 4 * n);
;                                 v[0][n] = (fq == 0) ? (v[0][n] * cs - pr * sn) : (v[0][n] * cs + pr * sn);
;                             }
;                         }
;                     }
;                     bf16_t* dst;
;                     if (pn < 2) dst = Q + (size_t)row * 512 + (4 * pn + wc) * 64 + 8 * fq;
;                     else { const int b = row >> 11, sq = row & (SEQ - 1); dst = KV + (size_t)slot * KV_SLOT + ((size_t)((b * 2 + gidx) * SEQ + sq)) * 64 + 8 * fq; }
; #pragma unroll
;                     for (int bj = 0; bj < 2; ++bj) store8(dst + 32 * bj, v[bj][0] * scale, v[bj][1] * scale);
.LBB0_441:
	s_mov_b32 s70, s64
	s_mov_b32 s71, s64
	v_lshl_add_u64 v[82:83], v[84:85], 0, v[156:157]
	v_pk_mul_f32 v[80:81], s[70:71], v[80:81]
	v_pk_mul_f32 v[78:79], s[64:65], v[78:79]
	v_pk_mul_f32 v[84:85], s[70:71], v[76:77]
	v_pk_mul_f32 v[76:77], s[64:65], v[74:75]
	v_cvt_pk_bf16_f32 v74, v78, v79
	v_cvt_pk_bf16_f32 v75, v80, v81
	v_cvt_pk_bf16_f32 v76, v76, v77
	v_cvt_pk_bf16_f32 v77, v84, v85
	v_pk_mul_f32 v[70:71], s[64:65], v[70:71]
	global_store_dwordx4 v[82:83], v[74:77], off
	v_pk_mul_f32 v[72:73], s[70:71], v[72:73]
	s_addk_i32 s28, 0x80
	v_pk_mul_f32 v[74:75], s[70:71], v[68:69]
	v_pk_mul_f32 v[68:69], s[64:65], v[66:67]
	v_cvt_pk_bf16_f32 v66, v70, v71
	v_fmamk_f32 v70, v194, 0x3a800000, v187
	v_rsq_f32_e32 v70, v70
	v_cvt_pk_bf16_f32 v67, v72, v73
	v_cvt_pk_bf16_f32 v68, v68, v69
	v_cvt_pk_bf16_f32 v69, v74, v75
	global_store_dwordx4 v[82:83], v[66:69], off offset:64
	v_pk_mul_f32 v[64:65], v[70:71], v[64:65] op_sel_hi:[0,1]
	v_pk_mul_f32 v[62:63], v[70:71], v[62:63] op_sel_hi:[0,1]
	v_or_b32_e32 v66, s28, v147
	v_pk_mul_f32 v[60:61], v[70:71], v[60:61] op_sel_hi:[0,1]
	v_pk_mul_f32 v[58:59], v[70:71], v[58:59] op_sel_hi:[0,1]
	v_pk_mul_f32 v[56:57], v[70:71], v[56:57] op_sel_hi:[0,1]
	v_pk_mul_f32 v[54:55], v[70:71], v[54:55] op_sel_hi:[0,1]
	v_pk_mul_f32 v[52:53], v[70:71], v[52:53] op_sel_hi:[0,1]
	s_and_b64 vcc, exec, s[10:11]
	v_pk_mul_f32 v[50:51], v[70:71], v[50:51] op_sel_hi:[0,1]
	s_cbranch_vccnz .LBB0_447
	v_lshlrev_b32_e32 v222, 6, v66
	v_and_b32_e32 v222, 0x1ffc0, v222
	global_load_dwordx4 v[206:209], v222, s[40:41] offset:32
	global_load_dwordx4 v[210:213], v222, s[40:41]
	global_load_dwordx4 v[214:217], v222, s[40:41] offset:48
	global_load_dwordx4 v[218:221], v222, s[40:41] offset:16
	v_pk_mul_f32 v[68:69], v[64:65], v[64:65]
	v_pk_mul_f32 v[70:71], v[62:63], v[62:63]
	v_mul_f32_e32 v67, v50, v50
	v_pk_mov_b32 v[72:73], v[70:71], v[68:69] op_sel:[1,0]
	v_mov_b32_e32 v71, v69
	v_pk_add_f32 v[68:69], v[72:73], v[70:71]
	v_pk_mul_f32 v[70:71], v[60:61], v[60:61]
	v_pk_mul_f32 v[72:73], v[58:59], v[58:59]
	v_pk_add_f32 v[68:69], v[68:69], v[68:69] op_sel:[0,1] op_sel_hi:[1,0]
	v_pk_mov_b32 v[74:75], v[72:73], v[70:71] op_sel:[1,0]
	v_mov_b32_e32 v73, v71
	v_pk_add_f32 v[70:71], v[74:75], v[72:73]
	v_mul_f32_e32 v72, v51, v51
	v_pk_add_f32 v[70:71], v[70:71], v[70:71] op_sel:[0,1] op_sel_hi:[1,0]
	v_mov_b32_e32 v69, v67
	v_mov_b32_e32 v71, v72
	v_pk_add_f32 v[68:69], v[68:69], v[70:71]
	v_mul_f32_e32 v70, v55, v55
	v_mul_f32_e32 v73, v52, v52
	v_pk_fma_f32 v[70:71], v[54:55], v[54:55], v[70:71] op_sel_hi:[1,1,0]
	v_mul_f32_e32 v72, v57, v57
	v_mul_f32_e32 v74, v53, v53
	v_mov_b32_e32 v71, v73
	v_pk_fma_f32 v[72:73], v[56:57], v[56:57], v[72:73] op_sel_hi:[1,1,0]
	v_xor_b32_e32 v67, 16, v190
	v_mov_b32_e32 v73, v74
	v_pk_add_f32 v[70:71], v[70:71], v[72:73]
	v_mov_b32_e32 v73, v157
	v_pk_add_f32 v[68:69], v[68:69], v[70:71]
	s_nop 0
	v_add_f32_e32 v68, v68, v69
	v_and_b32_e32 v69, 64, v190
	v_add_u32_e32 v69, 64, v69
	v_cmp_lt_i32_e32 vcc, v67, v69
	s_nop 1
	v_cndmask_b32_e32 v67, v190, v67, vcc
	v_lshlrev_b32_e32 v67, 2, v67
	ds_bpermute_b32 v70, v67, v68
	s_waitcnt lgkmcnt(0)
	v_add_f32_e32 v68, v68, v70
	v_xor_b32_e32 v70, 32, v190
	v_cmp_lt_i32_e32 vcc, v70, v69
	s_nop 1
	v_cndmask_b32_e32 v69, v190, v70, vcc
	v_lshlrev_b32_e32 v69, 2, v69
	ds_bpermute_b32 v69, v69, v68
	s_waitcnt lgkmcnt(0)
	v_add_f32_e32 v68, v68, v69
	v_fmamk_f32 v68, v68, 0x3c800000, v187
	v_rsq_f32_e32 v68, v68
	s_nop 0
	v_pk_mul_f32 v[62:63], v[62:63], v[68:69] op_sel_hi:[1,0]
	v_pk_mul_f32 v[64:65], v[64:65], v[68:69] op_sel_hi:[1,0]
	v_pk_mul_f32 v[62:63], v[142:143], v[62:63]
	v_pk_mul_f32 v[64:65], v[144:145], v[64:65]
	ds_bpermute_b32 v70, v67, v62
	ds_bpermute_b32 v71, v67, v63
	ds_bpermute_b32 v74, v67, v64
	ds_bpermute_b32 v75, v67, v65
	v_lshlrev_b32_e32 v69, 6, v66
	v_and_b32_e32 v72, 0x1f3c0, v69
	v_lshl_add_u64 v[72:73], s[40:41], 0, v[72:73]
	s_and_saveexec_b64 s[70:71], s[4:5]
	s_cbranch_execz .LBB0_444
	s_waitcnt vmcnt(2)
	v_mov_b64_e32 v[76:77], v[206:207]
	v_mov_b64_e32 v[78:79], v[208:209]
	v_mov_b64_e32 v[80:81], v[210:211]
	v_mov_b64_e32 v[82:83], v[212:213]
	s_waitcnt lgkmcnt(0)
	v_pk_mul_f32 v[74:75], v[78:79], v[74:75]
	v_pk_mul_f32 v[70:71], v[76:77], v[70:71]
	v_xor_b32_e32 v69, 0x80000000, v74
	v_xor_b32_e32 v76, 0x80000000, v75
	v_xor_b32_e32 v77, 0x80000000, v70
	v_xor_b32_e32 v78, 0x80000000, v71
	v_cndmask_b32_e64 v75, v75, v76, s[6:7]
	v_cndmask_b32_e64 v74, v74, v69, s[6:7]
	v_cndmask_b32_e64 v71, v71, v78, s[6:7]
	v_cndmask_b32_e64 v70, v70, v77, s[6:7]
	v_pk_fma_f32 v[64:65], v[64:65], v[82:83], v[74:75]
	v_pk_fma_f32 v[62:63], v[62:63], v[80:81], v[70:71]
.LBB0_444:
	s_or_b64 exec, exec, s[70:71]
	v_mov_b32_e32 v69, v68
	s_waitcnt lgkmcnt(3)
	v_mov_b32_e32 v70, v68
	s_waitcnt lgkmcnt(2)
	v_mov_b32_e32 v71, v68
	v_pk_mul_f32 v[60:61], v[60:61], v[70:71]
	v_pk_mul_f32 v[58:59], v[58:59], v[68:69]
	v_pk_mul_f32 v[60:61], v[140:141], v[60:61]
	v_pk_mul_f32 v[58:59], v[138:139], v[58:59]
	s_waitcnt lgkmcnt(1)
	ds_bpermute_b32 v74, v67, v58
	s_waitcnt lgkmcnt(1)
	ds_bpermute_b32 v75, v67, v59
	ds_bpermute_b32 v76, v67, v60
	ds_bpermute_b32 v77, v67, v61
	s_and_saveexec_b64 s[70:71], s[4:5]
	s_cbranch_execz .LBB0_446
	s_waitcnt vmcnt(0)
	v_mov_b64_e32 v[78:79], v[214:215]
	v_mov_b64_e32 v[80:81], v[216:217]
	v_mov_b64_e32 v[82:83], v[218:219]
	v_mov_b64_e32 v[84:85], v[220:221]
	s_waitcnt lgkmcnt(0)
	v_pk_mul_f32 v[72:73], v[80:81], v[76:77]
	v_pk_mul_f32 v[74:75], v[78:79], v[74:75]
	v_xor_b32_e32 v67, 0x80000000, v72
	v_xor_b32_e32 v76, 0x80000000, v73
	v_xor_b32_e32 v77, 0x80000000, v74
	v_xor_b32_e32 v78, 0x80000000, v75
	v_cndmask_b32_e64 v73, v73, v76, s[6:7]
	v_cndmask_b32_e64 v72, v72, v67, s[6:7]
	v_cndmask_b32_e64 v75, v75, v78, s[6:7]
	v_cndmask_b32_e64 v74, v74, v77, s[6:7]
	v_pk_fma_f32 v[60:61], v[60:61], v[84:85], v[72:73]
	v_pk_fma_f32 v[58:59], v[58:59], v[82:83], v[74:75]

;     DI void operator()(Acc& acc, const pg8::Unit& u, int wr, int wc, int fr, int fq, const Pre& pr) const {
;     ...
;                         float ss = 0.f;
; #pragma unroll
;                         for (int bj = 0; bj < 2; ++bj)
; #pragma unroll
;                             for (int n = 0; n < 2; ++n) ss += (v[bj][n][0] * v[bj][n][0] + v[bj][n][1] * v[bj][n][1]) + (v[bj][n][2] * v[bj][n][2] + v[bj][n][3] * v[bj][n][3]);
;                         ss += __shfl_xor(ss, 16); ss += __shfl_xor(ss, 32);
;                         const float hr = __builtin_amdgcn_rsqf(ss * (1.0f / 64.0f) + NORM_EPS);
; #pragma unroll
;                         for (int bj = 0; bj < 2; ++bj)
; #pragma unroll
;                             for (int n = 0; n < 2; ++n) v[bj][n] = v[bj][n] * hr * gn[bj][n];
;                         const int s = row & (SEQ - 1);
; #pragma unroll
;                         for (int n = 0; n < 2; ++n) {
;                             f32x4 pr;
; #pragma unroll
;                             for (int i = 0; i < 4; ++i) pr[i] = __shfl_xor(v[0][n][i], 16);
;                             if (fq < 2) {
;                                 const f32x4 cs = *(const f32x4*)(rope + s * 16 + 4 * n), sn = *(const f32x4*)(rope + s * 16 + 8 + 4 * n);
;                                 v[0][n] = (fq == 0) ? (v[0][n] * cs - pr * sn) : (v[0][n] * cs + pr * sn);
;                             }
;                         }
.LBB0_466:
	v_lshlrev_b32_e32 v222, 6, v98
	v_and_b32_e32 v222, 0x1ffc0, v222
	global_load_dwordx4 v[206:209], v222, s[40:41] offset:32
	global_load_dwordx4 v[210:213], v222, s[40:41]
	global_load_dwordx4 v[214:217], v222, s[40:41] offset:48
	global_load_dwordx4 v[218:221], v222, s[40:41] offset:16
	v_pk_mul_f32 v[100:101], v[96:97], v[96:97]
	v_pk_mul_f32 v[102:103], v[94:95], v[94:95]
	v_mul_f32_e32 v99, v82, v82
	v_pk_mov_b32 v[104:105], v[102:103], v[100:101] op_sel:[1,0]
	v_mov_b32_e32 v103, v101
	v_pk_add_f32 v[100:101], v[104:105], v[102:103]
	v_pk_mul_f32 v[102:103], v[92:93], v[92:93]
	v_pk_mul_f32 v[104:105], v[90:91], v[90:91]
	v_pk_add_f32 v[100:101], v[100:101], v[100:101] op_sel:[0,1] op_sel_hi:[1,0]
	v_pk_mov_b32 v[106:107], v[104:105], v[102:103] op_sel:[1,0]
	v_mov_b32_e32 v105, v103
	v_pk_add_f32 v[102:103], v[106:107], v[104:105]
	v_mul_f32_e32 v104, v83, v83
	v_pk_add_f32 v[102:103], v[102:103], v[102:103] op_sel:[0,1] op_sel_hi:[1,0]
	v_mov_b32_e32 v101, v99
	v_mov_b32_e32 v103, v104
	v_pk_add_f32 v[100:101], v[100:101], v[102:103]
	v_mul_f32_e32 v102, v87, v87
	v_mul_f32_e32 v105, v84, v84
	v_pk_fma_f32 v[102:103], v[86:87], v[86:87], v[102:103] op_sel_hi:[1,1,0]
	v_mul_f32_e32 v104, v89, v89
	v_mul_f32_e32 v106, v85, v85
	v_mov_b32_e32 v103, v105
	v_pk_fma_f32 v[104:105], v[88:89], v[88:89], v[104:105] op_sel_hi:[1,1,0]
	v_xor_b32_e32 v99, 16, v190
	v_mov_b32_e32 v105, v106
	v_pk_add_f32 v[102:103], v[102:103], v[104:105]
	v_mov_b32_e32 v105, v157
	v_pk_add_f32 v[100:101], v[100:101], v[102:103]
	s_nop 0
	v_add_f32_e32 v100, v100, v101
	v_and_b32_e32 v101, 64, v190
	v_add_u32_e32 v101, 64, v101
	v_cmp_lt_i32_e32 vcc, v99, v101
	s_nop 1
	v_cndmask_b32_e32 v99, v190, v99, vcc
	v_lshlrev_b32_e32 v99, 2, v99
	ds_bpermute_b32 v102, v99, v100
	s_waitcnt lgkmcnt(0)
	v_add_f32_e32 v100, v100, v102
	v_xor_b32_e32 v102, 32, v190
	v_cmp_lt_i32_e32 vcc, v102, v101
	s_nop 1
	v_cndmask_b32_e32 v101, v190, v102, vcc
	v_lshlrev_b32_e32 v101, 2, v101
	ds_bpermute_b32 v101, v101, v100
	s_waitcnt lgkmcnt(0)
	v_add_f32_e32 v100, v100, v101
	v_fmamk_f32 v100, v100, 0x3c800000, v187
	v_rsq_f32_e32 v100, v100
	s_nop 0
	v_pk_mul_f32 v[94:95], v[94:95], v[100:101] op_sel_hi:[1,0]
	v_pk_mul_f32 v[96:97], v[96:97], v[100:101] op_sel_hi:[1,0]
	v_pk_mul_f32 v[94:95], v[142:143], v[94:95]
	v_pk_mul_f32 v[96:97], v[144:145], v[96:97]
	ds_bpermute_b32 v102, v99, v94
	ds_bpermute_b32 v103, v99, v95
	ds_bpermute_b32 v106, v99, v96
	ds_bpermute_b32 v107, v99, v97
	v_lshlrev_b32_e32 v101, 6, v98
	v_and_b32_e32 v104, 0x1fbc0, v101
	v_lshl_add_u64 v[104:105], s[40:41], 0, v[104:105]
	s_and_saveexec_b64 s[70:71], s[4:5]
	s_cbranch_execz .LBB0_468
	s_waitcnt vmcnt(2)
	v_mov_b64_e32 v[108:109], v[206:207]
	v_mov_b64_e32 v[110:111], v[208:209]
	v_mov_b64_e32 v[112:113], v[210:211]
	v_mov_b64_e32 v[114:115], v[212:213]
	s_waitcnt lgkmcnt(0)
	v_pk_mul_f32 v[106:107], v[110:111], v[106:107]
	v_pk_mul_f32 v[102:103], v[108:109], v[102:103]
	v_xor_b32_e32 v101, 0x80000000, v106
	v_xor_b32_e32 v108, 0x80000000, v107
	v_xor_b32_e32 v109, 0x80000000, v102
	v_xor_b32_e32 v110, 0x80000000, v103
	v_cndmask_b32_e64 v107, v107, v108, s[6:7]
	v_cndmask_b32_e64 v106, v106, v101, s[6:7]
	v_cndmask_b32_e64 v103, v103, v110, s[6:7]
	v_cndmask_b32_e64 v102, v102, v109, s[6:7]
	v_pk_fma_f32 v[96:97], v[96:97], v[114:115], v[106:107]
	v_pk_fma_f32 v[94:95], v[94:95], v[112:113], v[102:103]
.LBB0_468:
	s_or_b64 exec, exec, s[70:71]
	v_mov_b32_e32 v101, v100
	s_waitcnt lgkmcnt(3)
	v_mov_b32_e32 v102, v100
	s_waitcnt lgkmcnt(2)
	v_mov_b32_e32 v103, v100
	v_pk_mul_f32 v[92:93], v[92:93], v[102:103]
	v_pk_mul_f32 v[90:91], v[90:91], v[100:101]
	v_pk_mul_f32 v[92:93], v[140:141], v[92:93]
	v_pk_mul_f32 v[90:91], v[138:139], v[90:91]
	s_waitcnt lgkmcnt(1)
	ds_bpermute_b32 v106, v99, v90
	s_waitcnt lgkmcnt(1)
	ds_bpermute_b32 v107, v99, v91
	ds_bpermute_b32 v108, v99, v92
	ds_bpermute_b32 v109, v99, v93
	s_and_saveexec_b64 s[70:71], s[4:5]
	s_cbranch_execz .LBB0_470
	s_waitcnt vmcnt(0)
	v_mov_b64_e32 v[110:111], v[214:215]
	v_mov_b64_e32 v[112:113], v[216:217]
	v_mov_b64_e32 v[114:115], v[218:219]
	v_mov_b64_e32 v[116:117], v[220:221]
	s_waitcnt lgkmcnt(0)
	v_pk_mul_f32 v[104:105], v[112:113], v[108:109]
	v_pk_mul_f32 v[106:107], v[110:111], v[106:107]
	v_xor_b32_e32 v99, 0x80000000, v104
	v_xor_b32_e32 v108, 0x80000000, v105
	v_xor_b32_e32 v109, 0x80000000, v106
	v_xor_b32_e32 v110, 0x80000000, v107
	v_cndmask_b32_e64 v105, v105, v108, s[6:7]
	v_cndmask_b32_e64 v104, v104, v99, s[6:7]
	v_cndmask_b32_e64 v107, v107, v110, s[6:7]
	v_cndmask_b32_e64 v106, v106, v109, s[6:7]
	v_pk_fma_f32 v[92:93], v[92:93], v[116:117], v[104:105]
	v_pk_fma_f32 v[90:91], v[90:91], v[114:115], v[106:107]

;     DI void operator()(Acc& acc, const pg8::Unit& u, int wr, int wc, int fr, int fq, const Pre& pr) const {
;     ...
;                         float ss = 0.f;
; #pragma unroll
;                         for (int bj = 0; bj < 2; ++bj)
; #pragma unroll
;                             for (int n = 0; n < 2; ++n) ss += (v[bj][n][0] * v[bj][n][0] + v[bj][n][1] * v[bj][n][1]) + (v[bj][n][2] * v[bj][n][2] + v[bj][n][3] * v[bj][n][3]);
;                         ss += __shfl_xor(ss, 16); ss += __shfl_xor(ss, 32);
;                         const float hr = __builtin_amdgcn_rsqf(ss * (1.0f / 64.0f) + NORM_EPS);
; #pragma unroll
;                         for (int bj = 0; bj < 2; ++bj)
; #pragma unroll
;                             for (int n = 0; n < 2; ++n) v[bj][n] = v[bj][n] * hr * gn[bj][n];
;                         const int s = row & (SEQ - 1);
; #pragma unroll
;                         for (int n = 0; n < 2; ++n) {
;                             f32x4 pr;
; #pragma unroll
;                             for (int i = 0; i < 4; ++i) pr[i] = __shfl_xor(v[0][n][i], 16);
;                             if (fq < 2) {
;                                 const f32x4 cs = *(const f32x4*)(rope + s * 16 + 4 * n), sn = *(const f32x4*)(rope + s * 16 + 8 + 4 * n);
;                                 v[0][n] = (fq == 0) ? (v[0][n] * cs - pr * sn) : (v[0][n] * cs + pr * sn);
;                             }
;                         }
.LBB0_472:
	v_lshlrev_b32_e32 v222, 6, v82
	v_and_b32_e32 v222, 0x1ffc0, v222
	global_load_dwordx4 v[206:209], v222, s[40:41] offset:32
	global_load_dwordx4 v[210:213], v222, s[40:41]
	global_load_dwordx4 v[214:217], v222, s[40:41] offset:48
	global_load_dwordx4 v[218:221], v222, s[40:41] offset:16
	v_pk_mul_f32 v[84:85], v[80:81], v[80:81]
	v_pk_mul_f32 v[86:87], v[78:79], v[78:79]
	v_mul_f32_e32 v83, v66, v66
	v_pk_mov_b32 v[88:89], v[86:87], v[84:85] op_sel:[1,0]
	v_mov_b32_e32 v87, v85
	v_pk_add_f32 v[84:85], v[88:89], v[86:87]
	v_pk_mul_f32 v[86:87], v[76:77], v[76:77]
	v_pk_mul_f32 v[88:89], v[74:75], v[74:75]
	v_pk_add_f32 v[84:85], v[84:85], v[84:85] op_sel:[0,1] op_sel_hi:[1,0]
	v_pk_mov_b32 v[90:91], v[88:89], v[86:87] op_sel:[1,0]
	v_mov_b32_e32 v89, v87
	v_pk_add_f32 v[86:87], v[90:91], v[88:89]
	v_mul_f32_e32 v88, v67, v67
	v_pk_add_f32 v[86:87], v[86:87], v[86:87] op_sel:[0,1] op_sel_hi:[1,0]
	v_mov_b32_e32 v85, v83
	v_mov_b32_e32 v87, v88
	v_pk_add_f32 v[84:85], v[84:85], v[86:87]
	v_mul_f32_e32 v86, v71, v71
	v_mul_f32_e32 v89, v68, v68
	v_pk_fma_f32 v[86:87], v[70:71], v[70:71], v[86:87] op_sel_hi:[1,1,0]
	v_mul_f32_e32 v88, v73, v73
	v_mul_f32_e32 v90, v69, v69
	v_mov_b32_e32 v87, v89
	v_pk_fma_f32 v[88:89], v[72:73], v[72:73], v[88:89] op_sel_hi:[1,1,0]
	v_xor_b32_e32 v83, 16, v190
	v_mov_b32_e32 v89, v90
	v_pk_add_f32 v[86:87], v[86:87], v[88:89]
	v_mov_b32_e32 v89, v157
	v_pk_add_f32 v[84:85], v[84:85], v[86:87]
	s_nop 0
	v_add_f32_e32 v84, v84, v85
	v_and_b32_e32 v85, 64, v190
	v_add_u32_e32 v85, 64, v85
	v_cmp_lt_i32_e32 vcc, v83, v85
	s_nop 1
	v_cndmask_b32_e32 v83, v190, v83, vcc
	v_lshlrev_b32_e32 v83, 2, v83
	ds_bpermute_b32 v86, v83, v84
	s_waitcnt lgkmcnt(0)
	v_add_f32_e32 v84, v84, v86
	v_xor_b32_e32 v86, 32, v190
	v_cmp_lt_i32_e32 vcc, v86, v85
	s_nop 1
	v_cndmask_b32_e32 v85, v190, v86, vcc
	v_lshlrev_b32_e32 v85, 2, v85
	ds_bpermute_b32 v85, v85, v84
	s_waitcnt lgkmcnt(0)
	v_add_f32_e32 v84, v84, v85
	v_fmamk_f32 v84, v84, 0x3c800000, v187
	v_rsq_f32_e32 v84, v84
	s_nop 0
	v_pk_mul_f32 v[78:79], v[78:79], v[84:85] op_sel_hi:[1,0]
	v_pk_mul_f32 v[80:81], v[80:81], v[84:85] op_sel_hi:[1,0]
	v_pk_mul_f32 v[78:79], v[142:143], v[78:79]
	v_pk_mul_f32 v[80:81], v[144:145], v[80:81]
	ds_bpermute_b32 v86, v83, v78
	ds_bpermute_b32 v87, v83, v79
	ds_bpermute_b32 v90, v83, v80
	ds_bpermute_b32 v91, v83, v81
	v_lshlrev_b32_e32 v85, 6, v82
	v_and_b32_e32 v88, 0x1ffc0, v85
	v_lshl_add_u64 v[88:89], s[40:41], 0, v[88:89]
	s_and_saveexec_b64 s[70:71], s[4:5]
	s_cbranch_execz .LBB0_474
	s_waitcnt vmcnt(2)
	v_mov_b64_e32 v[92:93], v[206:207]
	v_mov_b64_e32 v[94:95], v[208:209]
	v_mov_b64_e32 v[96:97], v[210:211]
	v_mov_b64_e32 v[98:99], v[212:213]
	s_waitcnt lgkmcnt(0)
	v_pk_mul_f32 v[90:91], v[94:95], v[90:91]
	v_pk_mul_f32 v[86:87], v[92:93], v[86:87]
	v_xor_b32_e32 v85, 0x80000000, v90
	v_xor_b32_e32 v92, 0x80000000, v91
	v_xor_b32_e32 v93, 0x80000000, v86
	v_xor_b32_e32 v94, 0x80000000, v87
	v_cndmask_b32_e64 v91, v91, v92, s[6:7]
	v_cndmask_b32_e64 v90, v90, v85, s[6:7]
	v_cndmask_b32_e64 v87, v87, v94, s[6:7]
	v_cndmask_b32_e64 v86, v86, v93, s[6:7]
	v_pk_fma_f32 v[80:81], v[80:81], v[98:99], v[90:91]
	v_pk_fma_f32 v[78:79], v[78:79], v[96:97], v[86:87]
.LBB0_474:
	s_or_b64 exec, exec, s[70:71]
	v_mov_b32_e32 v85, v84
	s_waitcnt lgkmcnt(3)
	v_mov_b32_e32 v86, v84
	s_waitcnt lgkmcnt(2)
	v_mov_b32_e32 v87, v84
	v_pk_mul_f32 v[76:77], v[76:77], v[86:87]
	v_pk_mul_f32 v[74:75], v[74:75], v[84:85]
	v_pk_mul_f32 v[76:77], v[140:141], v[76:77]
	v_pk_mul_f32 v[74:75], v[138:139], v[74:75]
	s_waitcnt lgkmcnt(1)
	ds_bpermute_b32 v90, v83, v74
	s_waitcnt lgkmcnt(1)
	ds_bpermute_b32 v91, v83, v75
	ds_bpermute_b32 v92, v83, v76
	ds_bpermute_b32 v93, v83, v77
	s_and_saveexec_b64 s[70:71], s[4:5]
	s_cbranch_execz .LBB0_476
	s_waitcnt vmcnt(0)
	v_mov_b64_e32 v[94:95], v[214:215]
	v_mov_b64_e32 v[96:97], v[216:217]
	v_mov_b64_e32 v[98:99], v[218:219]
	v_mov_b64_e32 v[100:101], v[220:221]
	s_waitcnt lgkmcnt(0)
	v_pk_mul_f32 v[88:89], v[96:97], v[92:93]
	v_pk_mul_f32 v[90:91], v[94:95], v[90:91]
	v_xor_b32_e32 v83, 0x80000000, v88
	v_xor_b32_e32 v92, 0x80000000, v89
	v_xor_b32_e32 v93, 0x80000000, v90
	v_xor_b32_e32 v94, 0x80000000, v91
	v_cndmask_b32_e64 v89, v89, v92, s[6:7]
	v_cndmask_b32_e64 v88, v88, v83, s[6:7]
	v_cndmask_b32_e64 v91, v91, v94, s[6:7]
	v_cndmask_b32_e64 v90, v90, v93, s[6:7]
	v_pk_fma_f32 v[76:77], v[76:77], v[100:101], v[88:89]
	v_pk_fma_f32 v[74:75], v[74:75], v[98:99], v[90:91]

;     DI void operator()(Acc& acc, const pg8::Unit& u, int wr, int wc, int fr, int fq, const Pre& pr) const {
;     ...
;                         float ss = 0.f;
; #pragma unroll
;                         for (int bj = 0; bj < 2; ++bj)
; #pragma unroll
;                             for (int n = 0; n < 2; ++n) ss += (v[bj][n][0] * v[bj][n][0] + v[bj][n][1] * v[bj][n][1]) + (v[bj][n][2] * v[bj][n][2] + v[bj][n][3] * v[bj][n][3]);
;                         ss += __shfl_xor(ss, 16); ss += __shfl_xor(ss, 32);
;                         const float hr = __builtin_amdgcn_rsqf(ss * (1.0f / 64.0f) + NORM_EPS);
; #pragma unroll
;                         for (int bj = 0; bj < 2; ++bj)
; #pragma unroll
;                             for (int n = 0; n < 2; ++n) v[bj][n] = v[bj][n] * hr * gn[bj][n];
;                         const int s = row & (SEQ - 1);
; #pragma unroll
;                         for (int n = 0; n < 2; ++n) {
;                             f32x4 pr;
; #pragma unroll
;                             for (int i = 0; i < 4; ++i) pr[i] = __shfl_xor(v[0][n][i], 16);
;                             if (fq < 2) {
;                                 const f32x4 cs = *(const f32x4*)(rope + s * 16 + 4 * n), sn = *(const f32x4*)(rope + s * 16 + 8 + 4 * n);
;                                 v[0][n] = (fq == 0) ? (v[0][n] * cs - pr * sn) : (v[0][n] * cs + pr * sn);
;                             }
;                         }
.LBB0_478:
	v_lshlrev_b32_e32 v222, 6, v50
	v_and_b32_e32 v222, 0x1ffc0, v222
	global_load_dwordx4 v[206:209], v222, s[40:41] offset:32
	global_load_dwordx4 v[210:213], v222, s[40:41]
	global_load_dwordx4 v[214:217], v222, s[40:41] offset:48
	global_load_dwordx4 v[218:221], v222, s[40:41] offset:16
	v_pk_mul_f32 v[52:53], v[48:49], v[48:49]
	v_pk_mul_f32 v[54:55], v[46:47], v[46:47]
	v_mul_f32_e32 v51, v34, v34
	v_pk_mov_b32 v[56:57], v[54:55], v[52:53] op_sel:[1,0]
	v_mov_b32_e32 v55, v53
	v_pk_add_f32 v[52:53], v[56:57], v[54:55]
	v_pk_mul_f32 v[54:55], v[44:45], v[44:45]
	v_pk_mul_f32 v[56:57], v[42:43], v[42:43]
	v_pk_add_f32 v[52:53], v[52:53], v[52:53] op_sel:[0,1] op_sel_hi:[1,0]
	v_pk_mov_b32 v[58:59], v[56:57], v[54:55] op_sel:[1,0]
	v_mov_b32_e32 v57, v55
	v_pk_add_f32 v[54:55], v[58:59], v[56:57]
	v_mul_f32_e32 v56, v35, v35
	v_pk_add_f32 v[54:55], v[54:55], v[54:55] op_sel:[0,1] op_sel_hi:[1,0]
	v_mov_b32_e32 v53, v51
	v_mov_b32_e32 v55, v56
	v_pk_add_f32 v[52:53], v[52:53], v[54:55]
	v_mul_f32_e32 v54, v39, v39
	v_mul_f32_e32 v57, v36, v36
	v_pk_fma_f32 v[54:55], v[38:39], v[38:39], v[54:55] op_sel_hi:[1,1,0]
	v_mul_f32_e32 v56, v41, v41
	v_mul_f32_e32 v58, v37, v37
	v_mov_b32_e32 v55, v57
	v_pk_fma_f32 v[56:57], v[40:41], v[40:41], v[56:57] op_sel_hi:[1,1,0]
	v_xor_b32_e32 v51, 16, v190
	v_mov_b32_e32 v57, v58
	v_pk_add_f32 v[54:55], v[54:55], v[56:57]
	v_mov_b32_e32 v57, v157
	v_pk_add_f32 v[52:53], v[52:53], v[54:55]
	s_nop 0
	v_add_f32_e32 v52, v52, v53
	v_and_b32_e32 v53, 64, v190
	v_add_u32_e32 v53, 64, v53
	v_cmp_lt_i32_e32 vcc, v51, v53
	s_nop 1
	v_cndmask_b32_e32 v51, v190, v51, vcc
	v_lshlrev_b32_e32 v51, 2, v51
	ds_bpermute_b32 v54, v51, v52
	s_waitcnt lgkmcnt(0)
	v_add_f32_e32 v52, v52, v54
	v_xor_b32_e32 v54, 32, v190
	v_cmp_lt_i32_e32 vcc, v54, v53
	s_nop 1
	v_cndmask_b32_e32 v53, v190, v54, vcc
	v_lshlrev_b32_e32 v53, 2, v53
	ds_bpermute_b32 v53, v53, v52
	s_waitcnt lgkmcnt(0)
	v_add_f32_e32 v52, v52, v53
	v_fmamk_f32 v52, v52, 0x3c800000, v187
	v_rsq_f32_e32 v52, v52
	s_nop 0
	v_pk_mul_f32 v[46:47], v[46:47], v[52:53] op_sel_hi:[1,0]
	v_pk_mul_f32 v[48:49], v[48:49], v[52:53] op_sel_hi:[1,0]
	v_pk_mul_f32 v[46:47], v[142:143], v[46:47]
	v_pk_mul_f32 v[48:49], v[144:145], v[48:49]
	ds_bpermute_b32 v54, v51, v46
	ds_bpermute_b32 v55, v51, v47
	ds_bpermute_b32 v58, v51, v48
	ds_bpermute_b32 v59, v51, v49
	v_lshlrev_b32_e32 v53, 6, v50
	v_and_b32_e32 v56, 0x1ffc0, v53
	v_lshl_add_u64 v[56:57], s[40:41], 0, v[56:57]
	s_and_saveexec_b64 s[70:71], s[4:5]
	s_cbranch_execz .LBB0_480
	s_waitcnt vmcnt(2)
	v_mov_b64_e32 v[60:61], v[206:207]
	v_mov_b64_e32 v[62:63], v[208:209]
	v_mov_b64_e32 v[68:69], v[210:211]
	v_mov_b64_e32 v[70:71], v[212:213]
	s_waitcnt lgkmcnt(0)
	v_pk_mul_f32 v[58:59], v[62:63], v[58:59]
	v_pk_mul_f32 v[54:55], v[60:61], v[54:55]
	v_xor_b32_e32 v53, 0x80000000, v58
	v_xor_b32_e32 v60, 0x80000000, v59
	v_xor_b32_e32 v61, 0x80000000, v54
	v_xor_b32_e32 v62, 0x80000000, v55
	v_cndmask_b32_e64 v59, v59, v60, s[6:7]
	v_cndmask_b32_e64 v58, v58, v53, s[6:7]
	v_cndmask_b32_e64 v55, v55, v62, s[6:7]
	v_cndmask_b32_e64 v54, v54, v61, s[6:7]
	v_pk_fma_f32 v[48:49], v[48:49], v[70:71], v[58:59]
	v_pk_fma_f32 v[46:47], v[46:47], v[68:69], v[54:55]
.LBB0_480:
	s_or_b64 exec, exec, s[70:71]
	v_mov_b32_e32 v53, v52
	s_waitcnt lgkmcnt(3)
	v_mov_b32_e32 v54, v52
	s_waitcnt lgkmcnt(2)
	v_mov_b32_e32 v55, v52
	v_pk_mul_f32 v[44:45], v[44:45], v[54:55]
	v_pk_mul_f32 v[42:43], v[42:43], v[52:53]
	v_pk_mul_f32 v[44:45], v[140:141], v[44:45]
	v_pk_mul_f32 v[42:43], v[138:139], v[42:43]
	s_waitcnt lgkmcnt(1)
	ds_bpermute_b32 v58, v51, v42
	s_waitcnt lgkmcnt(1)
	ds_bpermute_b32 v59, v51, v43
	ds_bpermute_b32 v60, v51, v44
	ds_bpermute_b32 v61, v51, v45
	s_and_saveexec_b64 s[70:71], s[4:5]
	s_cbranch_execz .LBB0_482
	s_waitcnt vmcnt(0)
	v_mov_b64_e32 v[62:63], v[214:215]
	v_mov_b64_e32 v[64:65], v[216:217]
	v_mov_b64_e32 v[68:69], v[218:219]
	v_mov_b64_e32 v[70:71], v[220:221]
	s_waitcnt lgkmcnt(0)
	v_pk_mul_f32 v[56:57], v[64:65], v[60:61]
	v_pk_mul_f32 v[58:59], v[62:63], v[58:59]
	v_xor_b32_e32 v51, 0x80000000, v56
	v_xor_b32_e32 v60, 0x80000000, v57
	v_xor_b32_e32 v61, 0x80000000, v58
	v_xor_b32_e32 v62, 0x80000000, v59
	v_cndmask_b32_e64 v57, v57, v60, s[6:7]
	v_cndmask_b32_e64 v56, v56, v51, s[6:7]
	v_cndmask_b32_e64 v59, v59, v62, s[6:7]
	v_cndmask_b32_e64 v58, v58, v61, s[6:7]
	v_pk_fma_f32 v[44:45], v[44:45], v[70:71], v[56:57]
	v_pk_fma_f32 v[42:43], v[42:43], v[68:69], v[58:59]

;     DI void operator()(Acc& acc, const pg8::Unit& u, int wr, int wc, int fr, int fq, const Pre& pr) const {
;     ...
;                         float ss = 0.f;
; #pragma unroll
;                         for (int bj = 0; bj < 2; ++bj)
; #pragma unroll
;                             for (int n = 0; n < 2; ++n) ss += (v[bj][n][0] * v[bj][n][0] + v[bj][n][1] * v[bj][n][1]) + (v[bj][n][2] * v[bj][n][2] + v[bj][n][3] * v[bj][n][3]);
;                         ss += __shfl_xor(ss, 16); ss += __shfl_xor(ss, 32);
;                         const float hr = __builtin_amdgcn_rsqf(ss * (1.0f / 64.0f) + NORM_EPS);
; #pragma unroll
;                         for (int bj = 0; bj < 2; ++bj)
; #pragma unroll
;                             for (int n = 0; n < 2; ++n) v[bj][n] = v[bj][n] * hr * gn[bj][n];
;                         const int s = row & (SEQ - 1);
; #pragma unroll
;                         for (int n = 0; n < 2; ++n) {
;                             f32x4 pr;
; #pragma unroll
;                             for (int i = 0; i < 4; ++i) pr[i] = __shfl_xor(v[0][n][i], 16);
;                             if (fq < 2) {
;                                 const f32x4 cs = *(const f32x4*)(rope + s * 16 + 4 * n), sn = *(const f32x4*)(rope + s * 16 + 8 + 4 * n);
;                                 v[0][n] = (fq == 0) ? (v[0][n] * cs - pr * sn) : (v[0][n] * cs + pr * sn);
;                             }
;                         }
.LBB0_484:
	v_lshlrev_b32_e32 v222, 6, v34
	v_and_b32_e32 v222, 0x1ffc0, v222
	global_load_dwordx4 v[206:209], v222, s[40:41] offset:32
	global_load_dwordx4 v[210:213], v222, s[40:41]
	global_load_dwordx4 v[214:217], v222, s[40:41] offset:48
	global_load_dwordx4 v[218:221], v222, s[40:41] offset:16
	v_pk_mul_f32 v[36:37], v[32:33], v[32:33]
	v_pk_mul_f32 v[38:39], v[30:31], v[30:31]
	v_mul_f32_e32 v35, v18, v18
	v_pk_mov_b32 v[40:41], v[38:39], v[36:37] op_sel:[1,0]
	v_mov_b32_e32 v39, v37
	v_pk_add_f32 v[36:37], v[40:41], v[38:39]
	v_pk_mul_f32 v[38:39], v[28:29], v[28:29]
	v_pk_mul_f32 v[40:41], v[26:27], v[26:27]
	v_pk_add_f32 v[36:37], v[36:37], v[36:37] op_sel:[0,1] op_sel_hi:[1,0]
	v_pk_mov_b32 v[42:43], v[40:41], v[38:39] op_sel:[1,0]
	v_mov_b32_e32 v41, v39
	v_pk_add_f32 v[38:39], v[42:43], v[40:41]
	v_mul_f32_e32 v40, v19, v19
	v_pk_add_f32 v[38:39], v[38:39], v[38:39] op_sel:[0,1] op_sel_hi:[1,0]
	v_mov_b32_e32 v37, v35
	v_mov_b32_e32 v39, v40
	v_pk_add_f32 v[36:37], v[36:37], v[38:39]
	v_mul_f32_e32 v38, v23, v23
	v_mul_f32_e32 v41, v20, v20
	v_pk_fma_f32 v[38:39], v[22:23], v[22:23], v[38:39] op_sel_hi:[1,1,0]
	v_mul_f32_e32 v40, v25, v25
	v_mul_f32_e32 v42, v21, v21
	v_mov_b32_e32 v39, v41
	v_pk_fma_f32 v[40:41], v[24:25], v[24:25], v[40:41] op_sel_hi:[1,1,0]
	v_xor_b32_e32 v35, 16, v190
	v_mov_b32_e32 v41, v42
	v_pk_add_f32 v[38:39], v[38:39], v[40:41]
	v_mov_b32_e32 v41, v157
	v_pk_add_f32 v[36:37], v[36:37], v[38:39]
	s_nop 0
	v_add_f32_e32 v36, v36, v37
	v_and_b32_e32 v37, 64, v190
	v_add_u32_e32 v37, 64, v37
	v_cmp_lt_i32_e32 vcc, v35, v37
	s_nop 1
	v_cndmask_b32_e32 v35, v190, v35, vcc
	v_lshlrev_b32_e32 v35, 2, v35
	ds_bpermute_b32 v38, v35, v36
	s_waitcnt lgkmcnt(0)
	v_add_f32_e32 v36, v36, v38
	v_xor_b32_e32 v38, 32, v190
	v_cmp_lt_i32_e32 vcc, v38, v37
	s_nop 1
	v_cndmask_b32_e32 v37, v190, v38, vcc
	v_lshlrev_b32_e32 v37, 2, v37
	ds_bpermute_b32 v37, v37, v36
	s_waitcnt lgkmcnt(0)
	v_add_f32_e32 v36, v36, v37
	v_fmamk_f32 v36, v36, 0x3c800000, v187
	v_rsq_f32_e32 v36, v36
	s_nop 0
	v_pk_mul_f32 v[30:31], v[30:31], v[36:37] op_sel_hi:[1,0]
	v_pk_mul_f32 v[32:33], v[32:33], v[36:37] op_sel_hi:[1,0]
	v_pk_mul_f32 v[30:31], v[142:143], v[30:31]
	v_pk_mul_f32 v[32:33], v[144:145], v[32:33]
	ds_bpermute_b32 v38, v35, v30
	ds_bpermute_b32 v39, v35, v31
	ds_bpermute_b32 v42, v35, v32
	ds_bpermute_b32 v43, v35, v33
	v_lshlrev_b32_e32 v37, 6, v34
	v_and_b32_e32 v40, 0x1ffc0, v37
	v_lshl_add_u64 v[40:41], s[40:41], 0, v[40:41]
	s_and_saveexec_b64 s[70:71], s[4:5]
	s_cbranch_execz .LBB0_486
	s_waitcnt vmcnt(2)
	v_mov_b64_e32 v[44:45], v[206:207]
	v_mov_b64_e32 v[46:47], v[208:209]
	v_mov_b64_e32 v[48:49], v[210:211]
	v_mov_b64_e32 v[50:51], v[212:213]
	s_waitcnt lgkmcnt(0)
	v_pk_mul_f32 v[42:43], v[46:47], v[42:43]
	v_pk_mul_f32 v[38:39], v[44:45], v[38:39]
	v_xor_b32_e32 v37, 0x80000000, v42
	v_xor_b32_e32 v44, 0x80000000, v43
	v_xor_b32_e32 v45, 0x80000000, v38
	v_xor_b32_e32 v46, 0x80000000, v39
	v_cndmask_b32_e64 v43, v43, v44, s[6:7]
	v_cndmask_b32_e64 v42, v42, v37, s[6:7]
	v_cndmask_b32_e64 v39, v39, v46, s[6:7]
	v_cndmask_b32_e64 v38, v38, v45, s[6:7]
	v_pk_fma_f32 v[32:33], v[32:33], v[50:51], v[42:43]
	v_pk_fma_f32 v[30:31], v[30:31], v[48:49], v[38:39]
.LBB0_486:
	s_or_b64 exec, exec, s[70:71]
	v_mov_b32_e32 v37, v36
	s_waitcnt lgkmcnt(3)
	v_mov_b32_e32 v38, v36
	s_waitcnt lgkmcnt(2)
	v_mov_b32_e32 v39, v36
	v_pk_mul_f32 v[28:29], v[28:29], v[38:39]
	v_pk_mul_f32 v[26:27], v[26:27], v[36:37]
	v_pk_mul_f32 v[28:29], v[140:141], v[28:29]
	v_pk_mul_f32 v[26:27], v[138:139], v[26:27]
	s_waitcnt lgkmcnt(1)
	ds_bpermute_b32 v42, v35, v26
	s_waitcnt lgkmcnt(1)
	ds_bpermute_b32 v43, v35, v27
	ds_bpermute_b32 v44, v35, v28
	ds_bpermute_b32 v45, v35, v29
	s_and_saveexec_b64 s[70:71], s[4:5]
	s_cbranch_execz .LBB0_488
	s_waitcnt vmcnt(0)
	v_mov_b64_e32 v[46:47], v[214:215]
	v_mov_b64_e32 v[48:49], v[216:217]
	v_mov_b64_e32 v[50:51], v[218:219]
	v_mov_b64_e32 v[52:53], v[220:221]
	s_waitcnt lgkmcnt(0)
	v_pk_mul_f32 v[40:41], v[48:49], v[44:45]
	v_pk_mul_f32 v[42:43], v[46:47], v[42:43]
	v_xor_b32_e32 v35, 0x80000000, v40
	v_xor_b32_e32 v44, 0x80000000, v41
	v_xor_b32_e32 v45, 0x80000000, v42
	v_xor_b32_e32 v46, 0x80000000, v43
	v_cndmask_b32_e64 v41, v41, v44, s[6:7]
	v_cndmask_b32_e64 v40, v40, v35, s[6:7]
	v_cndmask_b32_e64 v43, v43, v46, s[6:7]
	v_cndmask_b32_e64 v42, v42, v45, s[6:7]
	v_pk_fma_f32 v[28:29], v[28:29], v[52:53], v[40:41]
	v_pk_fma_f32 v[26:27], v[26:27], v[50:51], v[42:43]

;     DI void operator()(Acc& acc, const pg8::Unit& u, int wr, int wc, int fr, int fq, const Pre& pr) const {
;     ...
;                         float ss = 0.f;
; #pragma unroll
;                         for (int bj = 0; bj < 2; ++bj)
; #pragma unroll
;                             for (int n = 0; n < 2; ++n) ss += (v[bj][n][0] * v[bj][n][0] + v[bj][n][1] * v[bj][n][1]) + (v[bj][n][2] * v[bj][n][2] + v[bj][n][3] * v[bj][n][3]);
;                         ss += __shfl_xor(ss, 16); ss += __shfl_xor(ss, 32);
;                         const float hr = __builtin_amdgcn_rsqf(ss * (1.0f / 64.0f) + NORM_EPS);
; #pragma unroll
;                         for (int bj = 0; bj < 2; ++bj)
; #pragma unroll
;                             for (int n = 0; n < 2; ++n) v[bj][n] = v[bj][n] * hr * gn[bj][n];
;                         const int s = row & (SEQ - 1);
; #pragma unroll
;                         for (int n = 0; n < 2; ++n) {
;                             f32x4 pr;
; #pragma unroll
;                             for (int i = 0; i < 4; ++i) pr[i] = __shfl_xor(v[0][n][i], 16);
;                             if (fq < 2) {
;                                 const f32x4 cs = *(const f32x4*)(rope + s * 16 + 4 * n), sn = *(const f32x4*)(rope + s * 16 + 8 + 4 * n);
;                                 v[0][n] = (fq == 0) ? (v[0][n] * cs - pr * sn) : (v[0][n] * cs + pr * sn);
;                             }
;                         }
.LBB0_490:
	v_lshlrev_b32_e32 v222, 6, v18
	v_and_b32_e32 v222, 0x1ffc0, v222
	global_load_dwordx4 v[206:209], v222, s[40:41] offset:32
	global_load_dwordx4 v[210:213], v222, s[40:41]
	global_load_dwordx4 v[214:217], v222, s[40:41] offset:48
	global_load_dwordx4 v[218:221], v222, s[40:41] offset:16
	v_pk_mul_f32 v[20:21], v[16:17], v[16:17]
	v_pk_mul_f32 v[22:23], v[14:15], v[14:15]
	v_mul_f32_e32 v19, v2, v2
	v_pk_mov_b32 v[24:25], v[22:23], v[20:21] op_sel:[1,0]
	v_mov_b32_e32 v23, v21
	v_pk_add_f32 v[20:21], v[24:25], v[22:23]
	v_pk_mul_f32 v[22:23], v[12:13], v[12:13]
	v_pk_mul_f32 v[24:25], v[10:11], v[10:11]
	v_pk_add_f32 v[20:21], v[20:21], v[20:21] op_sel:[0,1] op_sel_hi:[1,0]
	v_pk_mov_b32 v[26:27], v[24:25], v[22:23] op_sel:[1,0]
	v_mov_b32_e32 v25, v23
	v_pk_add_f32 v[22:23], v[26:27], v[24:25]
	v_mul_f32_e32 v24, v3, v3
	v_pk_add_f32 v[22:23], v[22:23], v[22:23] op_sel:[0,1] op_sel_hi:[1,0]
	v_mov_b32_e32 v21, v19
	v_mov_b32_e32 v23, v24
	v_pk_add_f32 v[20:21], v[20:21], v[22:23]
	v_mul_f32_e32 v22, v7, v7
	v_mul_f32_e32 v25, v4, v4
	v_pk_fma_f32 v[22:23], v[6:7], v[6:7], v[22:23] op_sel_hi:[1,1,0]
	v_mul_f32_e32 v24, v9, v9
	v_mul_f32_e32 v26, v5, v5
	v_mov_b32_e32 v23, v25
	v_pk_fma_f32 v[24:25], v[8:9], v[8:9], v[24:25] op_sel_hi:[1,1,0]
	v_xor_b32_e32 v19, 16, v190
	v_mov_b32_e32 v25, v26
	v_pk_add_f32 v[22:23], v[22:23], v[24:25]
	v_mov_b32_e32 v25, v157
	v_pk_add_f32 v[20:21], v[20:21], v[22:23]
	s_nop 0
	v_add_f32_e32 v20, v20, v21
	v_and_b32_e32 v21, 64, v190
	v_add_u32_e32 v21, 64, v21
	v_cmp_lt_i32_e32 vcc, v19, v21
	s_nop 1
	v_cndmask_b32_e32 v19, v190, v19, vcc
	v_lshlrev_b32_e32 v19, 2, v19
	ds_bpermute_b32 v22, v19, v20
	s_waitcnt lgkmcnt(0)
	v_add_f32_e32 v20, v20, v22
	v_xor_b32_e32 v22, 32, v190
	v_cmp_lt_i32_e32 vcc, v22, v21
	s_nop 1
	v_cndmask_b32_e32 v21, v190, v22, vcc
	v_lshlrev_b32_e32 v21, 2, v21
	ds_bpermute_b32 v21, v21, v20
	s_waitcnt lgkmcnt(0)
	v_add_f32_e32 v20, v20, v21
	v_fmamk_f32 v20, v20, 0x3c800000, v187
	v_rsq_f32_e32 v20, v20
	s_nop 0
	v_pk_mul_f32 v[14:15], v[14:15], v[20:21] op_sel_hi:[1,0]
	v_pk_mul_f32 v[16:17], v[16:17], v[20:21] op_sel_hi:[1,0]
	v_pk_mul_f32 v[14:15], v[142:143], v[14:15]
	v_pk_mul_f32 v[16:17], v[144:145], v[16:17]
	ds_bpermute_b32 v22, v19, v14
	ds_bpermute_b32 v23, v19, v15
	ds_bpermute_b32 v26, v19, v16
	ds_bpermute_b32 v27, v19, v17
	v_lshlrev_b32_e32 v21, 6, v18
	v_and_b32_e32 v24, 0x1ffc0, v21
	v_lshl_add_u64 v[24:25], s[40:41], 0, v[24:25]
	s_and_saveexec_b64 s[10:11], s[4:5]
	s_cbranch_execz .LBB0_492
	s_waitcnt vmcnt(2)
	v_mov_b64_e32 v[28:29], v[206:207]
	v_mov_b64_e32 v[30:31], v[208:209]
	v_mov_b64_e32 v[32:33], v[210:211]
	v_mov_b64_e32 v[34:35], v[212:213]
	s_waitcnt lgkmcnt(0)
	v_pk_mul_f32 v[26:27], v[30:31], v[26:27]
	v_pk_mul_f32 v[22:23], v[28:29], v[22:23]
	v_xor_b32_e32 v21, 0x80000000, v26
	v_xor_b32_e32 v28, 0x80000000, v27
	v_xor_b32_e32 v29, 0x80000000, v22
	v_xor_b32_e32 v30, 0x80000000, v23
	v_cndmask_b32_e64 v27, v27, v28, s[6:7]
	v_cndmask_b32_e64 v26, v26, v21, s[6:7]
	v_cndmask_b32_e64 v23, v23, v30, s[6:7]
	v_cndmask_b32_e64 v22, v22, v29, s[6:7]
	v_pk_fma_f32 v[16:17], v[16:17], v[34:35], v[26:27]
	v_pk_fma_f32 v[14:15], v[14:15], v[32:33], v[22:23]
.LBB0_492:
	s_or_b64 exec, exec, s[10:11]
	v_mov_b32_e32 v21, v20
	s_waitcnt lgkmcnt(3)
	v_mov_b32_e32 v22, v20
	s_waitcnt lgkmcnt(2)
	v_mov_b32_e32 v23, v20
	v_pk_mul_f32 v[12:13], v[12:13], v[22:23]
	v_pk_mul_f32 v[10:11], v[10:11], v[20:21]
	v_pk_mul_f32 v[12:13], v[140:141], v[12:13]
	v_pk_mul_f32 v[10:11], v[138:139], v[10:11]
	s_waitcnt lgkmcnt(1)
	ds_bpermute_b32 v26, v19, v10
	s_waitcnt lgkmcnt(1)
	ds_bpermute_b32 v27, v19, v11
	ds_bpermute_b32 v28, v19, v12
	ds_bpermute_b32 v29, v19, v13
	s_and_saveexec_b64 s[10:11], s[4:5]
	s_cbranch_execz .LBB0_494
	s_waitcnt vmcnt(0)
	v_mov_b64_e32 v[30:31], v[214:215]
	v_mov_b64_e32 v[32:33], v[216:217]
	v_mov_b64_e32 v[34:35], v[218:219]
	v_mov_b64_e32 v[36:37], v[220:221]
	s_waitcnt lgkmcnt(0)
	v_pk_mul_f32 v[24:25], v[32:33], v[28:29]
	v_pk_mul_f32 v[26:27], v[30:31], v[26:27]
	v_xor_b32_e32 v19, 0x80000000, v24
	v_xor_b32_e32 v28, 0x80000000, v25
	v_xor_b32_e32 v29, 0x80000000, v26
	v_xor_b32_e32 v30, 0x80000000, v27
	v_cndmask_b32_e64 v25, v25, v28, s[6:7]
	v_cndmask_b32_e64 v24, v24, v19, s[6:7]
	v_cndmask_b32_e64 v27, v27, v30, s[6:7]
	v_cndmask_b32_e64 v26, v26, v29, s[6:7]
	v_pk_fma_f32 v[12:13], v[12:13], v[36:37], v[24:25]
	v_pk_fma_f32 v[10:11], v[10:11], v[34:35], v[26:27]
